# fox row-sum l via v_dot2c_f32_bf16 on the packed bf16 P (f32 accumulate) instead of a ones-row 32x32x16 MFMA; plus fox skip threshold 94 nats
# speedup vs baseline: 1.0304x; 1.0020x over previous
; template <int MODE>
; __device__ __forceinline__ void attn_unit(const AttnArgs& A, int b, int head, int ub, ALAS unsigned char* lds) {
;     ...
;     bf16x8 onesf; { const short one_ = (r32 == 0) ? (short)0x3F80 : (short)0; onesf = (bf16x8){one_, one_, one_, one_, one_, one_, one_, one_}; }
.LBB0_421:
	v_cmp_eq_u32_e32 vcc, 0, v117
	v_lshrrev_b32_e32 v3, 2, v182
	v_lshlrev_b32_e32 v0, 2, v116
	v_cndmask_b32_e32 v2, 0, v211, vcc
	v_and_or_b32 v3, v3, 3, v0
	v_lshlrev_b32_e32 v4, 1, v182
	v_lshlrev_b32_e32 v5, 3, v182
	v_mad_u32_u24 v3, v3, s31, 0
	v_and_b32_e32 v4, 32, v4
	v_and_b32_e32 v5, 24, v5
	v_perm_b32 v170, v2, v2, s42
	v_add3_u32 v205, v3, v4, v5
	v_mov_b32_e32 v171, v170
	v_mov_b32_e32 v172, v170
	s_andn2_b64 vcc, exec, s[10:11]
	v_mov_b32_e32 v173, v170
	v_mov_b32_e32 v170, 0x3f803f80
	s_cbranch_vccnz .LBB0_423
	v_lshl_or_b32 v0, s21, 6, v0
	v_or_b32_e32 v2, 32, v0
	v_or_b32_e32 v3, 33, v0
	v_cmp_le_i32_e32 vcc, v2, v114
	v_or_b32_e32 v5, 34, v0
	v_or_b32_e32 v7, 35, v0
	v_cndmask_b32_e32 v54, v213, v66, vcc
	v_cmp_le_i32_e32 vcc, v3, v114
	v_or_b32_e32 v9, 40, v0
	v_or_b32_e32 v11, 41, v0
	v_cndmask_b32_e32 v55, v213, v67, vcc
	v_cmp_le_i32_e32 vcc, v5, v114
	v_or_b32_e32 v13, 42, v0
	v_or_b32_e32 v15, 43, v0
	v_cndmask_b32_e32 v56, v213, v68, vcc
	v_cmp_le_i32_e32 vcc, v7, v114
	v_or_b32_e32 v17, 48, v0
	v_or_b32_e32 v19, 49, v0
	v_cndmask_b32_e32 v57, v213, v69, vcc
	v_cmp_le_i32_e32 vcc, v9, v114
	v_or_b32_e32 v21, 50, v0
	v_or_b32_e32 v23, 51, v0
	v_cndmask_b32_e32 v58, v213, v70, vcc
	v_cmp_le_i32_e32 vcc, v11, v114
	v_or_b32_e32 v25, 56, v0
	v_or_b32_e32 v27, 57, v0
	v_cndmask_b32_e32 v59, v213, v71, vcc
	v_cmp_le_i32_e32 vcc, v13, v114
	v_or_b32_e32 v29, 58, v0
	v_or_b32_e32 v31, 59, v0
	v_cndmask_b32_e32 v60, v213, v72, vcc
	v_cmp_le_i32_e32 vcc, v15, v114
	v_or_b32_e32 v4, 2, v0
	v_or_b32_e32 v6, 3, v0
	v_cndmask_b32_e32 v15, v213, v73, vcc
	v_cmp_le_i32_e32 vcc, v17, v114
	v_or_b32_e32 v8, 8, v0
	v_or_b32_e32 v10, 9, v0
	v_cndmask_b32_e32 v61, v213, v74, vcc
	v_cmp_le_i32_e32 vcc, v19, v114
	v_or_b32_e32 v12, 10, v0
	v_or_b32_e32 v14, 11, v0
	v_cndmask_b32_e32 v62, v213, v75, vcc
	v_cmp_le_i32_e32 vcc, v21, v114
	v_or_b32_e32 v16, 16, v0
	v_or_b32_e32 v18, 17, v0
	v_cndmask_b32_e32 v76, v213, v76, vcc
	v_cmp_le_i32_e32 vcc, v23, v114
	v_or_b32_e32 v20, 18, v0
	v_or_b32_e32 v22, 19, v0
	v_cndmask_b32_e32 v77, v213, v77, vcc
	v_cmp_le_i32_e32 vcc, v25, v114
	v_or_b32_e32 v24, 24, v0
	v_or_b32_e32 v26, 25, v0
	v_cndmask_b32_e32 v78, v213, v78, vcc
	v_cmp_le_i32_e32 vcc, v27, v114
	v_or_b32_e32 v28, 26, v0
	v_or_b32_e32 v30, 27, v0
	v_cndmask_b32_e32 v79, v213, v79, vcc
	v_cmp_le_i32_e32 vcc, v29, v114
	s_lshr_b32 s10, s22, 31
	s_add_i32 s10, s22, s10
	v_cndmask_b32_e32 v80, v213, v80, vcc
	v_cmp_le_i32_e32 vcc, v31, v114
	s_mul_i32 s10, s10, 6
	s_sub_i32 s10, s21, s10
	v_cndmask_b32_e32 v81, v213, v81, vcc
	v_cmp_lt_i32_e32 vcc, v0, v114
	s_mulk_i32 s10, 0x2400
	s_nop 0
	v_cndmask_b32_e32 v2, v213, v35, vcc
	v_cmp_le_i32_e32 vcc, v0, v114
	v_exp_f32_e32 v35, v2
	s_nop 0
	v_cndmask_b32_e32 v0, v213, v34, vcc
	v_cmp_le_i32_e32 vcc, v4, v114
	v_exp_f32_e32 v34, v0
	v_add_u32_e32 v0, s10, v205
	v_cndmask_b32_e32 v3, v213, v36, vcc
	v_cmp_le_i32_e32 vcc, v6, v114
	v_exp_f32_e32 v36, v3
	v_cvt_pk_bf16_f32 v2, v34, v35
	v_cndmask_b32_e32 v4, v213, v37, vcc
	v_cmp_le_i32_e32 vcc, v8, v114
	v_exp_f32_e32 v37, v4
	s_nop 0
	v_cndmask_b32_e32 v5, v213, v38, vcc
	v_cmp_le_i32_e32 vcc, v10, v114
	v_exp_f32_e32 v38, v5
	v_cvt_pk_bf16_f32 v3, v36, v37
	v_cndmask_b32_e32 v6, v213, v39, vcc
	v_cmp_le_i32_e32 vcc, v12, v114
	v_exp_f32_e32 v39, v6
	s_nop 0
	v_cndmask_b32_e32 v7, v213, v40, vcc
	v_cmp_le_i32_e32 vcc, v14, v114
	v_exp_f32_e32 v40, v7
	v_cvt_pk_bf16_f32 v4, v38, v39
	v_cndmask_b32_e32 v8, v213, v41, vcc
	v_cmp_le_i32_e32 vcc, v16, v114
	v_exp_f32_e32 v41, v8
	s_nop 0
	v_cndmask_b32_e32 v9, v213, v42, vcc
	v_cmp_le_i32_e32 vcc, v18, v114
	v_exp_f32_e32 v42, v9
	v_cvt_pk_bf16_f32 v5, v40, v41
	v_cndmask_b32_e32 v10, v213, v43, vcc
	v_cmp_le_i32_e32 vcc, v20, v114
	v_exp_f32_e32 v43, v10
	s_nop 0
	v_cndmask_b32_e32 v11, v213, v44, vcc
	v_cmp_le_i32_e32 vcc, v22, v114
	v_exp_f32_e32 v44, v11
	v_cvt_pk_bf16_f32 v216, v42, v43
	v_cndmask_b32_e32 v12, v213, v45, vcc
	v_cmp_le_i32_e32 vcc, v24, v114
	v_exp_f32_e32 v45, v12
	s_nop 0
	v_cndmask_b32_e32 v13, v213, v46, vcc
	v_cmp_le_i32_e32 vcc, v26, v114
	v_exp_f32_e32 v46, v13
	v_cvt_pk_bf16_f32 v217, v44, v45
	v_cndmask_b32_e32 v14, v213, v47, vcc
	v_cmp_le_i32_e32 vcc, v28, v114
	v_exp_f32_e32 v47, v14
	s_nop 0
	v_cndmask_b32_e32 v16, v213, v48, vcc
	v_cmp_le_i32_e32 vcc, v30, v114
	ds_read_b64_tr_b16 v[6:7], v0 offset:55296
	ds_read_b64_tr_b16 v[8:9], v0 offset:56448
	ds_read_b64_tr_b16 v[12:13], v0 offset:56512
	ds_read_b64_tr_b16 v[10:11], v0 offset:55360
	ds_read_b64_tr_b16 v[114:115], v0 offset:57600
	ds_read_b64_tr_b16 v[116:117], v0 offset:58752
	ds_read_b64_tr_b16 v[52:53], v0 offset:58816
	ds_read_b64_tr_b16 v[50:51], v0 offset:57664
	v_cndmask_b32_e32 v17, v213, v49, vcc
	v_exp_f32_e32 v48, v16
	v_exp_f32_e32 v49, v17
	v_cvt_pk_bf16_f32 v218, v46, v47
	v_cvt_pk_bf16_f32 v219, v48, v49
	s_waitcnt lgkmcnt(4)
	v_mfma_f32_32x32x16_bf16 v[16:31], v[10:13], v[2:5], 0
	v_exp_f32_e32 v66, v54
	v_exp_f32_e32 v67, v55
	v_exp_f32_e32 v68, v56
	v_exp_f32_e32 v69, v57
	v_exp_f32_e32 v70, v58
	v_exp_f32_e32 v71, v59
	v_exp_f32_e32 v72, v60
	s_waitcnt lgkmcnt(0)
	v_mfma_f32_32x32x16_bf16 v[16:31], v[50:53], v[216:219], v[16:31]
	v_exp_f32_e32 v74, v61
	v_exp_f32_e32 v75, v62
	v_exp_f32_e32 v73, v15
	v_exp_f32_e32 v76, v76
	v_exp_f32_e32 v77, v77
	v_exp_f32_e32 v78, v78
	v_exp_f32_e32 v79, v79
	v_mfma_f32_32x32x16_bf16 v[50:65], v[6:9], v[2:5], 0
	v_exp_f32_e32 v80, v80
	v_exp_f32_e32 v81, v81
	v_cvt_pk_bf16_f32 v6, v66, v67
	v_cvt_pk_bf16_f32 v7, v68, v69
	v_cvt_pk_bf16_f32 v8, v70, v71
	v_cvt_pk_bf16_f32 v9, v72, v73
	v_cvt_pk_bf16_f32 v10, v74, v75
	v_mfma_f32_32x32x16_bf16 v[50:65], v[114:117], v[216:219], v[50:65]
	v_cvt_pk_bf16_f32 v11, v76, v77
	v_cvt_pk_bf16_f32 v12, v78, v79
	v_cvt_pk_bf16_f32 v13, v80, v81
	v_mov_b32_e32 v114, 0
	v_dot2c_f32_bf16_e32 v114, v2, v170
	v_dot2c_f32_bf16_e32 v114, v3, v170
	v_dot2c_f32_bf16_e32 v114, v4, v170
	v_dot2c_f32_bf16_e32 v114, v5, v170
	ds_read_b64_tr_b16 v[2:3], v0 offset:59904
	ds_read_b64_tr_b16 v[4:5], v0 offset:61056
	ds_read_b64_tr_b16 v[222:223], v0 offset:61120
	ds_read_b64_tr_b16 v[220:221], v0 offset:59968
	ds_read_b64_tr_b16 v[224:225], v0 offset:62208
	ds_read_b64_tr_b16 v[226:227], v0 offset:63360
	ds_read_b64_tr_b16 v[230:231], v0 offset:63424
	ds_read_b64_tr_b16 v[228:229], v0 offset:62272
	v_dot2c_f32_bf16_e32 v114, v216, v170
	v_dot2c_f32_bf16_e32 v114, v217, v170
	v_dot2c_f32_bf16_e32 v114, v218, v170
	v_dot2c_f32_bf16_e32 v114, v219, v170
	s_waitcnt lgkmcnt(6)
	v_mfma_f32_32x32x16_bf16 v[50:65], v[2:5], v[6:9], v[50:65]
	s_waitcnt lgkmcnt(4)
	v_mfma_f32_32x32x16_bf16 v[16:31], v[220:223], v[6:9], v[16:31]
	v_dot2c_f32_bf16_e32 v114, v6, v170
	v_dot2c_f32_bf16_e32 v114, v7, v170
	v_dot2c_f32_bf16_e32 v114, v8, v170
	v_dot2c_f32_bf16_e32 v114, v9, v170
	s_waitcnt lgkmcnt(2)
	v_mfma_f32_32x32x16_bf16 v[50:65], v[224:227], v[10:13], v[50:65]
	s_waitcnt lgkmcnt(0)
	v_mfma_f32_32x32x16_bf16 v[16:31], v[228:231], v[10:13], v[16:31]
	v_dot2c_f32_bf16_e32 v114, v10, v170
	v_dot2c_f32_bf16_e32 v114, v11, v170
	v_dot2c_f32_bf16_e32 v114, v12, v170
	v_dot2c_f32_bf16_e32 v114, v13, v170
	s_andn2_b64 vcc, exec, s[6:7]
	s_cbranch_vccz .LBB0_424
	s_branch .LBB0_309

.LBB0_435:
	s_mul_hi_i32 s8, s10, 0x2aaaaaab
	s_lshr_b32 s9, s8, 31
	s_add_i32 s8, s8, s9
	s_mul_i32 s8, s8, 6
	s_sub_i32 s8, s10, s8
	s_mulk_i32 s8, 0x2400
	v_add_u32_e32 v0, s8, v205
	ds_read_b64_tr_b16 v[6:7], v0 offset:55296
	ds_read_b64_tr_b16 v[8:9], v0 offset:56448
	ds_read_b64_tr_b16 v[12:13], v0 offset:56512
	ds_read_b64_tr_b16 v[10:11], v0 offset:55360
	ds_read_b64_tr_b16 v[216:217], v0 offset:57600
	ds_read_b64_tr_b16 v[218:219], v0 offset:58752
	ds_read_b64_tr_b16 v[222:223], v0 offset:58816
	ds_read_b64_tr_b16 v[220:221], v0 offset:57664
	v_exp_f32_e32 v82, v82
	v_exp_f32_e32 v83, v83
	v_exp_f32_e32 v84, v84
	v_exp_f32_e32 v85, v85
	v_exp_f32_e32 v86, v86
	v_exp_f32_e32 v87, v87
	v_exp_f32_e32 v88, v88
	v_exp_f32_e32 v89, v89
	v_exp_f32_e32 v90, v90
	v_exp_f32_e32 v91, v91
	v_exp_f32_e32 v92, v92
	v_exp_f32_e32 v93, v93
	v_exp_f32_e32 v94, v94
	v_exp_f32_e32 v95, v95
	v_exp_f32_e32 v96, v96
	v_exp_f32_e32 v97, v97
	v_cvt_pk_bf16_f32 v2, v82, v83
	v_cvt_pk_bf16_f32 v3, v84, v85
	v_cvt_pk_bf16_f32 v4, v86, v87
	v_cvt_pk_bf16_f32 v5, v88, v89
	v_cvt_pk_bf16_f32 v224, v90, v91
	v_cvt_pk_bf16_f32 v225, v92, v93
	v_cvt_pk_bf16_f32 v226, v94, v95
	v_cvt_pk_bf16_f32 v227, v96, v97
	s_waitcnt lgkmcnt(4)
	v_mfma_f32_32x32x16_bf16 v[16:31], v[10:13], v[2:5], v[16:31]
	v_exp_f32_e32 v98, v98
	v_exp_f32_e32 v99, v99
	v_exp_f32_e32 v100, v100
	v_exp_f32_e32 v101, v101
	v_exp_f32_e32 v102, v102
	v_exp_f32_e32 v103, v103
	v_exp_f32_e32 v104, v104
	v_mfma_f32_32x32x16_bf16 v[50:65], v[6:9], v[2:5], v[50:65]
	v_exp_f32_e32 v105, v105
	v_exp_f32_e32 v106, v106
	v_exp_f32_e32 v107, v107
	v_exp_f32_e32 v108, v108
	v_exp_f32_e32 v109, v109
	v_exp_f32_e32 v110, v110
	v_exp_f32_e32 v111, v111
	v_dot2c_f32_bf16_e32 v114, v2, v170
	v_dot2c_f32_bf16_e32 v114, v3, v170
	v_dot2c_f32_bf16_e32 v114, v4, v170
	v_dot2c_f32_bf16_e32 v114, v5, v170
	v_exp_f32_e32 v112, v112
	v_exp_f32_e32 v113, v113
	v_cvt_pk_bf16_f32 v6, v98, v99
	v_cvt_pk_bf16_f32 v7, v100, v101
	v_cvt_pk_bf16_f32 v8, v102, v103
	v_cvt_pk_bf16_f32 v9, v104, v105
	v_cvt_pk_bf16_f32 v10, v106, v107
	s_waitcnt lgkmcnt(0)
	v_mfma_f32_32x32x16_bf16 v[16:31], v[220:223], v[224:227], v[16:31]
	v_cvt_pk_bf16_f32 v11, v108, v109
	v_cvt_pk_bf16_f32 v12, v110, v111
	v_cvt_pk_bf16_f32 v13, v112, v113
	v_mfma_f32_32x32x16_bf16 v[50:65], v[216:219], v[224:227], v[50:65]
	ds_read_b64_tr_b16 v[2:3], v0 offset:59904
	ds_read_b64_tr_b16 v[4:5], v0 offset:61056
	ds_read_b64_tr_b16 v[218:219], v0 offset:61120
	ds_read_b64_tr_b16 v[216:217], v0 offset:59968
	ds_read_b64_tr_b16 v[220:221], v0 offset:62208
	ds_read_b64_tr_b16 v[222:223], v0 offset:63360
	ds_read_b64_tr_b16 v[230:231], v0 offset:63424
	ds_read_b64_tr_b16 v[228:229], v0 offset:62272
	v_dot2c_f32_bf16_e32 v114, v224, v170
	v_dot2c_f32_bf16_e32 v114, v225, v170
	v_dot2c_f32_bf16_e32 v114, v226, v170
	v_dot2c_f32_bf16_e32 v114, v227, v170
	s_waitcnt lgkmcnt(6)
	v_mfma_f32_32x32x16_bf16 v[50:65], v[2:5], v[6:9], v[50:65]
	s_waitcnt lgkmcnt(4)
	v_mfma_f32_32x32x16_bf16 v[16:31], v[216:219], v[6:9], v[16:31]
	v_dot2c_f32_bf16_e32 v114, v6, v170
	v_dot2c_f32_bf16_e32 v114, v7, v170
	v_dot2c_f32_bf16_e32 v114, v8, v170
	v_dot2c_f32_bf16_e32 v114, v9, v170
	s_waitcnt lgkmcnt(2)
	v_mfma_f32_32x32x16_bf16 v[50:65], v[220:223], v[10:13], v[50:65]
	s_waitcnt lgkmcnt(0)
	v_mfma_f32_32x32x16_bf16 v[16:31], v[228:231], v[10:13], v[16:31]
	v_dot2c_f32_bf16_e32 v114, v10, v170
	v_dot2c_f32_bf16_e32 v114, v11, v170
	v_dot2c_f32_bf16_e32 v114, v12, v170
	v_dot2c_f32_bf16_e32 v114, v13, v170
	s_andn2_b64 vcc, exec, s[6:7]
	s_cbranch_vccnz .LBB0_309

.LBB0_447:
	s_andn2_b64 vcc, exec, s[2:3]
	s_cbranch_vccnz .LBB0_449
	s_mul_hi_i32 s2, s10, 0x2aaaaaab
	s_lshr_b32 s3, s2, 31
	s_add_i32 s2, s2, s3
	s_mul_i32 s2, s2, 6
	s_sub_i32 s2, s10, s2
	s_mulk_i32 s2, 0x2400
	v_add_u32_e32 v0, s2, v205
	ds_read_b64_tr_b16 v[220:221], v0 offset:55296
	ds_read_b64_tr_b16 v[222:223], v0 offset:56448
	ds_read_b64_tr_b16 v[226:227], v0 offset:56512
	ds_read_b64_tr_b16 v[224:225], v0 offset:55360
	ds_read_b64_tr_b16 v[228:229], v0 offset:57600
	ds_read_b64_tr_b16 v[230:231], v0 offset:58752
	ds_read_b64_tr_b16 v[234:235], v0 offset:58816
	ds_read_b64_tr_b16 v[232:233], v0 offset:57664
	v_exp_f32_e32 v34, v34
	v_exp_f32_e32 v35, v35
	v_exp_f32_e32 v36, v36
	v_exp_f32_e32 v37, v37
	v_exp_f32_e32 v38, v38
	v_exp_f32_e32 v39, v39
	v_exp_f32_e32 v40, v40
	v_exp_f32_e32 v41, v41
	v_exp_f32_e32 v42, v42
	v_exp_f32_e32 v43, v43
	v_exp_f32_e32 v44, v44
	v_exp_f32_e32 v45, v45
	v_exp_f32_e32 v46, v46
	v_exp_f32_e32 v47, v47
	v_exp_f32_e32 v48, v48
	v_exp_f32_e32 v49, v49
	v_cvt_pk_bf16_f32 v216, v34, v35
	v_cvt_pk_bf16_f32 v217, v36, v37
	v_cvt_pk_bf16_f32 v218, v38, v39
	v_cvt_pk_bf16_f32 v219, v40, v41
	v_cvt_pk_bf16_f32 v236, v42, v43
	v_cvt_pk_bf16_f32 v237, v44, v45
	v_cvt_pk_bf16_f32 v238, v46, v47
	v_cvt_pk_bf16_f32 v239, v48, v49
	s_waitcnt lgkmcnt(4)
	v_mfma_f32_32x32x16_bf16 v[16:31], v[224:227], v[216:219], v[16:31]
	v_exp_f32_e32 v66, v66
	v_exp_f32_e32 v67, v67
	v_exp_f32_e32 v68, v68
	v_exp_f32_e32 v69, v69
	v_exp_f32_e32 v70, v70
	v_exp_f32_e32 v71, v71
	v_exp_f32_e32 v72, v72
	v_mfma_f32_32x32x16_bf16 v[50:65], v[220:223], v[216:219], v[50:65]
	v_exp_f32_e32 v73, v73
	v_exp_f32_e32 v74, v74
	v_exp_f32_e32 v75, v75
	v_exp_f32_e32 v76, v76
	v_exp_f32_e32 v77, v77
	v_exp_f32_e32 v78, v78
	v_exp_f32_e32 v79, v79
	v_dot2c_f32_bf16_e32 v114, v216, v170
	v_dot2c_f32_bf16_e32 v114, v217, v170
	v_dot2c_f32_bf16_e32 v114, v218, v170
	v_dot2c_f32_bf16_e32 v114, v219, v170
	v_exp_f32_e32 v80, v80
	v_exp_f32_e32 v81, v81
	v_cvt_pk_bf16_f32 v220, v66, v67
	v_cvt_pk_bf16_f32 v221, v68, v69
	v_cvt_pk_bf16_f32 v222, v70, v71
	v_cvt_pk_bf16_f32 v223, v72, v73
	v_cvt_pk_bf16_f32 v224, v74, v75
	s_waitcnt lgkmcnt(0)
	v_mfma_f32_32x32x16_bf16 v[16:31], v[232:235], v[236:239], v[16:31]
	v_cvt_pk_bf16_f32 v225, v76, v77
	v_cvt_pk_bf16_f32 v226, v78, v79
	v_cvt_pk_bf16_f32 v227, v80, v81
	v_mfma_f32_32x32x16_bf16 v[50:65], v[228:231], v[236:239], v[50:65]
	ds_read_b64_tr_b16 v[216:217], v0 offset:59904
	ds_read_b64_tr_b16 v[218:219], v0 offset:61056
	ds_read_b64_tr_b16 v[230:231], v0 offset:61120
	ds_read_b64_tr_b16 v[228:229], v0 offset:59968
	ds_read_b64_tr_b16 v[232:233], v0 offset:62208
	ds_read_b64_tr_b16 v[234:235], v0 offset:63360
	ds_read_b64_tr_b16 v[242:243], v0 offset:63424
	ds_read_b64_tr_b16 v[240:241], v0 offset:62272
	v_dot2c_f32_bf16_e32 v114, v236, v170
	v_dot2c_f32_bf16_e32 v114, v237, v170
	v_dot2c_f32_bf16_e32 v114, v238, v170
	v_dot2c_f32_bf16_e32 v114, v239, v170
	s_waitcnt lgkmcnt(6)
	v_mfma_f32_32x32x16_bf16 v[50:65], v[216:219], v[220:223], v[50:65]
	s_waitcnt lgkmcnt(4)
	v_mfma_f32_32x32x16_bf16 v[16:31], v[228:231], v[220:223], v[16:31]
	v_dot2c_f32_bf16_e32 v114, v220, v170
	v_dot2c_f32_bf16_e32 v114, v221, v170
	v_dot2c_f32_bf16_e32 v114, v222, v170
	v_dot2c_f32_bf16_e32 v114, v223, v170
	s_waitcnt lgkmcnt(2)
	v_mfma_f32_32x32x16_bf16 v[50:65], v[232:235], v[224:227], v[50:65]
	s_waitcnt lgkmcnt(0)
	v_mfma_f32_32x32x16_bf16 v[16:31], v[240:243], v[224:227], v[16:31]
	v_dot2c_f32_bf16_e32 v114, v224, v170
	v_dot2c_f32_bf16_e32 v114, v225, v170
	v_dot2c_f32_bf16_e32 v114, v226, v170
	v_dot2c_f32_bf16_e32 v114, v227, v170

.LBB0_459:
	s_andn2_b64 vcc, exec, s[6:7]
	s_cbranch_vccnz .LBB0_461
	s_mul_hi_i32 s6, s10, 0x2aaaaaab
	s_lshr_b32 s7, s6, 31
	s_add_i32 s6, s6, s7
	s_mul_i32 s6, s6, 6
	s_sub_i32 s6, s10, s6
	s_mulk_i32 s6, 0x2400
	v_add_u32_e32 v0, s6, v205
	ds_read_b64_tr_b16 v[220:221], v0 offset:55296
	ds_read_b64_tr_b16 v[222:223], v0 offset:56448
	ds_read_b64_tr_b16 v[226:227], v0 offset:56512
	ds_read_b64_tr_b16 v[224:225], v0 offset:55360
	ds_read_b64_tr_b16 v[228:229], v0 offset:57600
	ds_read_b64_tr_b16 v[230:231], v0 offset:58752
	ds_read_b64_tr_b16 v[234:235], v0 offset:58816
	ds_read_b64_tr_b16 v[232:233], v0 offset:57664
	v_exp_f32_e32 v82, v82
	v_exp_f32_e32 v83, v83
	v_exp_f32_e32 v84, v84
	v_exp_f32_e32 v85, v85
	v_exp_f32_e32 v86, v86
	v_exp_f32_e32 v87, v87
	v_exp_f32_e32 v88, v88
	v_exp_f32_e32 v89, v89
	v_exp_f32_e32 v90, v90
	v_exp_f32_e32 v91, v91
	v_exp_f32_e32 v92, v92
	v_exp_f32_e32 v93, v93
	v_exp_f32_e32 v94, v94
	v_exp_f32_e32 v95, v95
	v_exp_f32_e32 v96, v96
	v_exp_f32_e32 v97, v97
	v_cvt_pk_bf16_f32 v216, v82, v83
	v_cvt_pk_bf16_f32 v217, v84, v85
	v_cvt_pk_bf16_f32 v218, v86, v87
	v_cvt_pk_bf16_f32 v219, v88, v89
	v_cvt_pk_bf16_f32 v236, v90, v91
	v_cvt_pk_bf16_f32 v237, v92, v93
	v_cvt_pk_bf16_f32 v238, v94, v95
	v_cvt_pk_bf16_f32 v239, v96, v97
	s_waitcnt lgkmcnt(4)
	v_mfma_f32_32x32x16_bf16 v[16:31], v[224:227], v[216:219], v[16:31]
	v_exp_f32_e32 v98, v98
	v_exp_f32_e32 v99, v99
	v_exp_f32_e32 v100, v100
	v_exp_f32_e32 v101, v101
	v_exp_f32_e32 v102, v102
	v_exp_f32_e32 v103, v103
	v_exp_f32_e32 v104, v104
	v_mfma_f32_32x32x16_bf16 v[50:65], v[220:223], v[216:219], v[50:65]
	v_exp_f32_e32 v105, v105
	v_exp_f32_e32 v106, v106
	v_exp_f32_e32 v107, v107
	v_exp_f32_e32 v108, v108
	v_exp_f32_e32 v109, v109
	v_exp_f32_e32 v110, v110
	v_exp_f32_e32 v111, v111
	v_dot2c_f32_bf16_e32 v114, v216, v170
	v_dot2c_f32_bf16_e32 v114, v217, v170
	v_dot2c_f32_bf16_e32 v114, v218, v170
	v_dot2c_f32_bf16_e32 v114, v219, v170
	v_exp_f32_e32 v112, v112
	v_exp_f32_e32 v113, v113
	v_cvt_pk_bf16_f32 v220, v98, v99
	v_cvt_pk_bf16_f32 v221, v100, v101
	v_cvt_pk_bf16_f32 v222, v102, v103
	v_cvt_pk_bf16_f32 v223, v104, v105
	v_cvt_pk_bf16_f32 v224, v106, v107
	s_waitcnt lgkmcnt(0)
	v_mfma_f32_32x32x16_bf16 v[16:31], v[232:235], v[236:239], v[16:31]
	v_cvt_pk_bf16_f32 v225, v108, v109
	v_cvt_pk_bf16_f32 v226, v110, v111
	v_cvt_pk_bf16_f32 v227, v112, v113
	v_mfma_f32_32x32x16_bf16 v[50:65], v[228:231], v[236:239], v[50:65]
	ds_read_b64_tr_b16 v[216:217], v0 offset:59904
	ds_read_b64_tr_b16 v[218:219], v0 offset:61056
	ds_read_b64_tr_b16 v[230:231], v0 offset:61120
	ds_read_b64_tr_b16 v[228:229], v0 offset:59968
	ds_read_b64_tr_b16 v[232:233], v0 offset:62208
	ds_read_b64_tr_b16 v[234:235], v0 offset:63360
	ds_read_b64_tr_b16 v[242:243], v0 offset:63424
	ds_read_b64_tr_b16 v[240:241], v0 offset:62272
	v_dot2c_f32_bf16_e32 v114, v236, v170
	v_dot2c_f32_bf16_e32 v114, v237, v170
	v_dot2c_f32_bf16_e32 v114, v238, v170
	v_dot2c_f32_bf16_e32 v114, v239, v170
	s_waitcnt lgkmcnt(6)
	v_mfma_f32_32x32x16_bf16 v[50:65], v[216:219], v[220:223], v[50:65]
	s_waitcnt lgkmcnt(4)
	v_mfma_f32_32x32x16_bf16 v[16:31], v[228:231], v[220:223], v[16:31]
	v_dot2c_f32_bf16_e32 v114, v220, v170
	v_dot2c_f32_bf16_e32 v114, v221, v170
	v_dot2c_f32_bf16_e32 v114, v222, v170
	v_dot2c_f32_bf16_e32 v114, v223, v170
	s_waitcnt lgkmcnt(2)
	v_mfma_f32_32x32x16_bf16 v[50:65], v[232:235], v[224:227], v[50:65]
	s_waitcnt lgkmcnt(0)
	v_mfma_f32_32x32x16_bf16 v[16:31], v[240:243], v[224:227], v[16:31]
	v_dot2c_f32_bf16_e32 v114, v224, v170
	v_dot2c_f32_bf16_e32 v114, v225, v170
	v_dot2c_f32_bf16_e32 v114, v226, v170
	v_dot2c_f32_bf16_e32 v114, v227, v170
